# P3 one ticket stream (tail items continue the attention counter, no separate first tail fetch); P2 cumsum WGs issue the two magnitude loads with the LF loads
# baseline (speedup 1.0000x reference)
.LBB0_182:
	s_cmp_lt_i32 s90, 3
	s_cselect_b64 s[4:5], -1, 0
	s_add_u32 s60, s88, 0x4200000
	s_addc_u32 s61, s89, 0
	s_and_b64 s[6:7], s[4:5], s[0:1]
	s_andn2_b64 vcc, exec, s[6:7]
	s_cbranch_vccnz .LBB0_260
	v_mov_b32_e32 v18, v254
	s_cmp_gt_i32 s2, 15
	s_cbranch_scc1 .LBB0_201
	v_and_b32_e32 v20, 63, v18
	v_lshlrev_b32_e32 v34, 2, v20
	global_load_dword v35, v34, s[68:69]
	global_load_dword v34, v34, s[70:71]
	s_lshl_b32 s0, s76, 10
	s_ashr_i32 s3, s2, 31
	v_lshl_or_b32 v4, v20, 4, s0
	s_lshl_b64 s[0:1], s[2:3], 15
	s_add_u32 s0, s12, s0
	v_mov_b32_e32 v22, 0
	s_addc_u32 s1, s13, s1
	v_mov_b32_e32 v5, v22
	v_lshl_add_u64 v[10:11], v[4:5], 2, s[0:1]
	global_load_dwordx4 v[0:3], v[10:11], off
	global_load_dwordx4 v[6:9], v[10:11], off offset:16
	global_load_dwordx4 v[24:27], v[10:11], off offset:32
	global_load_dwordx4 v[28:31], v[10:11], off offset:48
	v_mbcnt_lo_u32_b32 v10, -1, 0
	v_mbcnt_hi_u32_b32 v19, -1, v10
	v_and_b32_e32 v21, 64, v19
	v_add_u32_e32 v10, -1, v19
	v_cmp_lt_i32_e32 vcc, v10, v21
	s_waitcnt vmcnt(3)
	v_add_f32_e32 v1, v0, v1
	v_add_f32_e32 v16, v1, v2
	v_add_f32_e32 v17, v16, v3
	s_waitcnt vmcnt(2)
	v_add_f32_e32 v14, v17, v6
	v_add_f32_e32 v15, v14, v7
	v_add_f32_e32 v12, v15, v8
	v_cndmask_b32_e32 v10, v10, v19, vcc
	v_add_f32_e32 v13, v12, v9
	v_lshlrev_b32_e32 v23, 2, v10
	s_waitcnt vmcnt(1)
	v_add_f32_e32 v10, v13, v24
	v_add_f32_e32 v11, v10, v25
	v_add_f32_e32 v8, v11, v26
	v_add_f32_e32 v9, v8, v27
	s_waitcnt vmcnt(0)
	v_add_f32_e32 v6, v9, v28
	v_add_f32_e32 v7, v6, v29
	v_add_f32_e32 v2, v7, v30
	v_add_f32_e32 v3, v2, v31
	ds_bpermute_b32 v23, v23, v3
	v_add_u32_e32 v24, -2, v19
	v_cmp_lt_i32_e32 vcc, v24, v21
	v_add_u32_e32 v25, -4, v19
	s_waitcnt lgkmcnt(0)
	v_add_f32_e32 v23, v3, v23
	v_cndmask_b32_e32 v24, v24, v19, vcc
	v_cmp_eq_u32_e32 vcc, 0, v20
	v_lshlrev_b32_e32 v24, 2, v24
	s_nop 0
	v_cndmask_b32_e32 v23, v23, v3, vcc
	ds_bpermute_b32 v24, v24, v23
	v_cmp_lt_i32_e32 vcc, v25, v21
	s_waitcnt lgkmcnt(0)
	v_add_f32_e32 v24, v23, v24
	v_cndmask_b32_e32 v25, v25, v19, vcc
	v_cmp_gt_u32_e32 vcc, 2, v20
	v_lshlrev_b32_e32 v25, 2, v25
	s_nop 0
	v_cndmask_b32_e32 v23, v24, v23, vcc
	ds_bpermute_b32 v24, v25, v23
	v_add_u32_e32 v25, -8, v19
	v_cmp_lt_i32_e32 vcc, v25, v21
	s_waitcnt lgkmcnt(0)
	v_add_f32_e32 v24, v23, v24
	v_cndmask_b32_e32 v25, v25, v19, vcc
	v_cmp_gt_u32_e32 vcc, 4, v20
	v_lshlrev_b32_e32 v25, 2, v25
	s_nop 0
	v_cndmask_b32_e32 v23, v24, v23, vcc
	ds_bpermute_b32 v24, v25, v23
	v_add_u32_e32 v25, -16, v19
	v_cmp_lt_i32_e32 vcc, v25, v21
	s_waitcnt lgkmcnt(0)
	v_add_f32_e32 v24, v23, v24
	v_cndmask_b32_e32 v25, v25, v19, vcc
	v_cmp_gt_u32_e32 vcc, 8, v20
	v_lshlrev_b32_e32 v25, 2, v25
	s_nop 0
	v_cndmask_b32_e32 v23, v24, v23, vcc
	ds_bpermute_b32 v24, v25, v23
	v_subrev_u32_e32 v25, 32, v19
	v_cmp_lt_i32_e32 vcc, v25, v21
	s_waitcnt lgkmcnt(0)
	v_add_f32_e32 v24, v23, v24
	v_cndmask_b32_e32 v25, v25, v19, vcc
	v_cmp_gt_u32_e32 vcc, 16, v20
	v_lshlrev_b32_e32 v25, 2, v25
	s_nop 0
	v_cndmask_b32_e32 v23, v24, v23, vcc
	ds_bpermute_b32 v24, v25, v23
	v_cmp_eq_u32_e32 vcc, 63, v20
	s_waitcnt lgkmcnt(0)
	v_add_f32_e32 v24, v23, v24
	s_and_saveexec_b64 s[0:1], vcc
	s_lshl_b32 s4, s76, 2
	s_add_i32 s4, s4, 0
	s_add_i32 s4, s4, 0x23000
	v_mov_b32_e32 v25, s4
	ds_write_b32 v25, v24
	s_or_b64 exec, exec, s[0:1]
	v_readlane_b32 s0, v255, 4
	s_cmp_lt_u32 s0, 64
	s_waitcnt lgkmcnt(0)
	s_barrier
	s_cbranch_scc1 .LBB0_194
	s_add_i32 s0, s76, -1
	s_cmp_lt_u32 s0, 7
	s_cbranch_scc1 .LBB0_190
	s_mov_b32 s1, 0
	s_add_i32 s4, 0, 0x23000
	s_and_b32 s0, s76, 0x3fffff8
	v_mov_b32_e32 v22, 0

.LBB0_194:
	s_lshl_b64 s[0:1], s[2:3], 13
	v_cmp_gt_u32_e32 vcc, 32, v20
	s_lshl_b64 s[0:1], s[0:1], 2
	s_add_u32 s0, s88, s0
	v_cndmask_b32_e32 v23, v24, v23, vcc
	v_sub_f32_e32 v23, v23, v3
	s_addc_u32 s1, s89, s1
	v_add_f32_e32 v26, v23, v22
	v_lshl_add_u64 v[28:29], v[4:5], 2, s[0:1]
	s_mov_b64 s[0:1], 0x180000
	v_lshl_add_u64 v[30:31], v[28:29], 0, s[0:1]
	v_pk_add_f32 v[0:1], v[26:27], v[0:1] op_sel_hi:[0,1]
	s_mov_b32 s0, 0xbfb8aa3b
	v_pk_mul_f32 v[22:23], v[0:1], s[0:1] op_sel_hi:[1,0]
	v_pk_add_f32 v[0:1], v[26:27], v[16:17] op_sel_hi:[0,1]
	v_pk_mul_f32 v[24:25], v[0:1], s[0:1] op_sel_hi:[1,0]
	s_mov_b32 s1, 0x180000
	v_add_co_u32_e32 v0, vcc, s1, v28
	v_pk_add_f32 v[2:3], v[26:27], v[2:3] op_sel_hi:[0,1]
	s_nop 0
	v_addc_co_u32_e32 v1, vcc, 0, v29, vcc
	global_store_dwordx4 v[0:1], v[22:25], off
	v_pk_add_f32 v[0:1], v[26:27], v[14:15] op_sel_hi:[0,1]
	v_pk_mul_f32 v[14:15], v[0:1], s[0:1] op_sel_hi:[1,0]
	v_pk_add_f32 v[0:1], v[26:27], v[12:13] op_sel_hi:[0,1]
	v_pk_mul_f32 v[16:17], v[0:1], s[0:1] op_sel_hi:[1,0]
	v_pk_add_f32 v[0:1], v[26:27], v[10:11] op_sel_hi:[0,1]
	v_pk_mul_f32 v[10:11], v[0:1], s[0:1] op_sel_hi:[1,0]
	v_pk_add_f32 v[0:1], v[26:27], v[8:9] op_sel_hi:[0,1]
	v_pk_mul_f32 v[12:13], v[0:1], s[0:1] op_sel_hi:[1,0]
	v_pk_add_f32 v[0:1], v[26:27], v[6:7] op_sel_hi:[0,1]
	v_pk_mul_f32 v[0:1], v[0:1], s[0:1] op_sel_hi:[1,0]
	v_pk_mul_f32 v[2:3], v[2:3], s[0:1] op_sel_hi:[1,0]
	global_store_dwordx4 v[30:31], v[14:17], off offset:16
	global_store_dwordx4 v[30:31], v[10:13], off offset:32
	global_store_dwordx4 v[30:31], v[0:3], off offset:48
	v_add_u32_e32 v7, 64, v21
	v_xor_b32_e32 v8, 1, v19
	v_cmp_lt_i32_e32 vcc, v8, v7
	v_xor_b32_e32 v9, 2, v19
	v_xor_b32_e32 v20, 4, v19
	v_cndmask_b32_e32 v8, v19, v8, vcc
	v_lshlrev_b32_e32 v8, 2, v8
	v_cmp_lt_i32_e32 vcc, v9, v7
	v_xor_b32_e32 v21, 8, v19
	v_xor_b32_e32 v26, 16, v19
	v_cndmask_b32_e32 v9, v19, v9, vcc
	v_lshlrev_b32_e32 v9, 2, v9
	v_cmp_lt_i32_e32 vcc, v20, v7
	v_xor_b32_e32 v27, 32, v19
	v_lshl_add_u32 v4, v4, 2, 0
	v_cndmask_b32_e32 v20, v19, v20, vcc
	v_lshlrev_b32_e32 v20, 2, v20
	v_cmp_lt_i32_e32 vcc, v21, v7
	ds_write_b128 v4, v[22:25]
	ds_write_b128 v4, v[14:17] offset:16
	ds_write_b128 v4, v[10:13] offset:32
	ds_write_b128 v4, v[0:3] offset:48
	v_cndmask_b32_e32 v21, v19, v21, vcc
	v_cmp_lt_i32_e32 vcc, v26, v7
	s_waitcnt lgkmcnt(0)
	s_barrier
	v_cndmask_b32_e32 v26, v19, v26, vcc
	v_cmp_lt_i32_e32 vcc, v27, v7
	v_and_b32_e32 v28, 0x7fffffff, v35
	v_and_b32_e32 v29, 0x7fffffff, v34
	ds_bpermute_b32 v28, v8, v28
	ds_bpermute_b32 v8, v8, v29
	v_max_f32_e64 v6, |v35|, |v35|
	v_max_f32_e64 v5, |v34|, |v34|
	v_cndmask_b32_e32 v7, v19, v27, vcc
	s_waitcnt lgkmcnt(1)
	v_max_f32_e32 v28, v28, v28
	s_waitcnt lgkmcnt(0)
	v_max_f32_e32 v8, v8, v8
	v_max_f32_e32 v6, v6, v28
	v_max_f32_e32 v5, v5, v8
	ds_bpermute_b32 v8, v9, v6
	ds_bpermute_b32 v9, v9, v5
	v_lshlrev_b32_e32 v19, 2, v21
	v_lshlrev_b32_e32 v7, 2, v7
	v_cmp_gt_i32_e32 vcc, 32, v18
	s_waitcnt lgkmcnt(1)
	v_max_f32_e32 v8, v8, v8
	s_waitcnt lgkmcnt(0)
	v_max_f32_e32 v9, v9, v9
	v_max_f32_e32 v6, v6, v8
	v_max_f32_e32 v5, v5, v9
	ds_bpermute_b32 v8, v20, v6
	ds_bpermute_b32 v9, v20, v5
	s_waitcnt lgkmcnt(1)
	v_max_f32_e32 v8, v8, v8
	s_waitcnt lgkmcnt(0)
	v_max_f32_e32 v9, v9, v9
	v_max_f32_e32 v6, v6, v8
	v_max_f32_e32 v5, v5, v9
	ds_bpermute_b32 v8, v19, v6
	ds_bpermute_b32 v9, v19, v5
	v_lshlrev_b32_e32 v19, 2, v26
	s_waitcnt lgkmcnt(1)
	v_max_f32_e32 v8, v8, v8
	s_waitcnt lgkmcnt(0)
	v_max_f32_e32 v9, v9, v9
	v_max_f32_e32 v6, v6, v8
	v_max_f32_e32 v5, v5, v9
	ds_bpermute_b32 v8, v19, v6
	ds_bpermute_b32 v9, v19, v5
	s_waitcnt lgkmcnt(1)
	v_max_f32_e32 v0, v8, v8
	s_waitcnt lgkmcnt(0)
	v_max_f32_e32 v2, v9, v9
	v_max_f32_e32 v1, v6, v0
	v_max_f32_e32 v0, v5, v2
	ds_bpermute_b32 v4, v7, v1
	ds_bpermute_b32 v3, v7, v0
	s_and_saveexec_b64 s[0:1], vcc
	s_cbranch_execz .LBB0_200
	v_lshl_add_u32 v2, v18, 2, 4
	v_ashrrev_i32_e32 v5, 1, v2
	v_cmp_lt_i32_e32 vcc, 2, v5
	v_mov_b32_e32 v2, 0
	s_and_saveexec_b64 s[4:5], vcc
	s_cbranch_execz .LBB0_199
	s_waitcnt lgkmcnt(1)
	v_max_f32_e32 v2, v4, v4
	v_max_f32_e32 v1, v1, v2
	s_waitcnt lgkmcnt(0)
	v_max_f32_e32 v2, v3, v3
	v_max_f32_e32 v2, v0, v2
	v_lshl_add_u32 v0, v18, 10, 0
	ds_read_b32 v0, v0
	v_mul_f32_e32 v1, 0x41000000, v1
	v_mul_f32_e32 v1, v2, v1
	v_mul_f32_e32 v1, 0x3f828f5c, v1
	v_mul_f32_e32 v1, 0x3fb8aa3b, v1
	v_fmaak_f32 v2, 2.0, v1, 0x42000000
	v_add_u32_e32 v3, -2, v5
	v_mov_b32_e32 v1, 0
	s_mov_b64 s[8:9], 0

.LBB0_408:
	s_add_i32 s18, s6, s33
	s_sub_i32 s18, s18, 0x200
	v_mov_b32_e32 v0, v252
	v_mov_b32_e32 v25, 0
	v_and_b32_e32 v2, 63, v0
	v_lshlrev_b32_e32 v24, 4, v2
	v_cmp_eq_u32_e64 s[4:5], 0, v0
	v_lshl_add_u64 v[0:1], s[88:89], 0, v[24:25]
	s_mov_b64 s[0:1], 0x5200000
	v_lshl_add_u64 v[26:27], v[0:1], 0, s[0:1]
	s_mov_b64 s[0:1], 0x6200000
	v_lshl_add_u64 v[30:31], s[60:61], 0, v[24:25]
	v_lshl_add_u64 v[32:33], s[94:95], 0, v[24:25]
	v_lshlrev_b32_e32 v24, 5, v2
	v_lshl_add_u64 v[28:29], v[0:1], 0, s[0:1]
	v_lshl_add_u64 v[34:35], s[66:67], 0, v[24:25]
	s_mov_b64 s[0:1], 0x1000
	v_lshlrev_b32_e32 v0, 6, v2
	v_mov_b32_e32 v1, v25
	v_cmp_eq_u32_e64 s[6:7], 0, v2
	v_lshl_add_u64 v[36:37], v[34:35], 0, s[0:1]
	v_or_b32_e32 v2, 0x3000, v0
	v_lshl_add_u64 v[0:1], s[14:15], 0, v[0:1]
	s_mov_b64 s[0:1], 0x9000
	s_lshl_b32 s3, s76, 3
	v_mov_b32_e32 v3, v25
	v_lshl_add_u64 v[42:43], v[0:1], 0, s[0:1]
	v_mbcnt_lo_u32_b32 v0, -1, 0
	v_mov_b32_e32 v254, v252
	s_add_i32 s16, s3, 0xffffc000
	v_lshl_add_u64 v[38:39], s[58:59], 0, v[2:3]
	v_lshl_add_u64 v[40:41], s[14:15], 0, v[2:3]
	s_mov_b64 s[0:1], 0x1000000
	v_mov_b32_e32 v92, 0x40000
	v_mov_b32_e32 v93, 0x45000
	s_mov_b64 s[8:9], 0x800
	s_add_i32 s17, 0, 0x1f000
	v_mbcnt_hi_u32_b32 v94, -1, v0
	s_branch .LBB0_412
.LBB0_409:
	s_or_b64 exec, exec, s[12:13]
	s_waitcnt vmcnt(0)
	v_readfirstlane_b32 s12, v1
	s_add_i32 s12, s33, s12
	s_add_i32 s12, s12, s33
	s_sub_i32 s12, s12, 0x200
	v_mov_b32_e32 v1, s17
	v_add_u32_e32 v0, s12, v0
	ds_write_b32 v1, v0

.LBB0_427:
	s_and_saveexec_b64 s[10:11], s[4:5]
	s_xor_b64 s[10:11], exec, s[10:11]
	s_cbranch_execz .LBB0_410
	s_mov_b64 s[14:15], exec
	v_mbcnt_lo_u32_b32 v0, s14, 0
	v_mbcnt_hi_u32_b32 v0, s15, v0
	v_cmp_eq_u32_e32 vcc, 0, v0
	s_and_saveexec_b64 s[12:13], vcc
	s_cbranch_execz .LBB0_409
	s_bcnt1_i32_b64 s14, s[14:15]
	v_mov_b32_e32 v1, s14
	global_atomic_add v1, v25, v1, s[88:89] offset:512 sc0
	s_branch .LBB0_409
